# v059 + static s_setprio 1 for waves 4-7 in the neighbourhood-attention loop
# baseline (speedup 1.0000x reference)
; #define SHX(v, m) __int_as_float(__builtin_amdgcn_ds_bpermute(((LANE ^ (m)) << 2), __float_as_int(v)))
; template <int DQK, int QT, bool NA> ...
;     ...
;   if (NA) {
;     na_rq = na_r0 + (wid >> 2);
;     na_cq = (wid & 3) * 16 + l15;
;     na_cs = min(max(na_cq - 8, 0), 48);
;     na_rs = min(max(na_rq - 4, 0), 56);
;   }
;   const int na_rlo = NA ? min(max(na_r0 - 4, 0), 56) : 0;
;     ...
;             if (NA && !isctx) {
;               int ck = kt * 16 + quad * 4 + j;
;               bool valid = (ck >= na_cs) && (ck < na_cs + 16);
;               int bidx = (kr - na_rq + 7) * 31 + min(max(ck - na_cq + 15, 0), 30);
;               v = valid ? v + rpb[bidx] * 1.4426950408889634f : -1e30f;
;             }
;             s[kt][qt][j] = v;
;             mx = fmaxf(mx, v);
;           }
;         mx = fmaxf(mx, SHX(mx, 16));
;         mx = fmaxf(mx, SHX(mx, 32));
;         float mnew = fmaxf(mrun[qt], mx);
;         float alpha = __builtin_amdgcn_exp2f(mrun[qt] - mnew);
;         mrun[qt] = mnew;
;         float ls = 0.f;
; #pragma unroll
;         for (int kt = 0; kt < 4; ++kt)
; #pragma unroll
;           for (int j = 0; j < 4; ++j) {
;             float pv = __builtin_amdgcn_exp2f(s[kt][qt][j] - mnew);
;             ls += pv;
;             s[kt][qt][j] = pv;
;           }
;         lrun[qt] = lrun[qt] * alpha + ls;
.LBB0_725:
	v_add_f32_e32 v120, 0, v120
	v_add_f32_e32 v120, v121, v120
	v_add_f32_e32 v121, 0, v137
	v_add_f32_e32 v120, v122, v120
	v_add_f32_e32 v121, v138, v121
	v_add_f32_e32 v97, 0, v97
	v_add_f32_e32 v120, v123, v120
	v_add_f32_e32 v121, v139, v121
	v_add_f32_e32 v97, v154, v97
	v_add_f32_e32 v67, 0, v67
	v_add_f32_e32 v120, v124, v120
	v_add_f32_e32 v121, v140, v121
	v_add_f32_e32 v97, v155, v97
	v_add_f32_e32 v67, v68, v67
	v_add_f32_e32 v120, v125, v120
	v_add_f32_e32 v121, v141, v121
	v_add_f32_e32 v97, v156, v97
	v_add_f32_e32 v67, v69, v67
	v_add_f32_e32 v120, v126, v120
	v_add_f32_e32 v121, v142, v121
	v_add_f32_e32 v97, v157, v97
	v_add_f32_e32 v67, v70, v67
	v_add_f32_e32 v120, v127, v120
	v_add_f32_e32 v121, v143, v121
	v_add_f32_e32 v97, v158, v97
	v_add_f32_e32 v67, v71, v67
	v_add_f32_e32 v120, v128, v120
	v_add_f32_e32 v121, v144, v121
	v_add_f32_e32 v97, v159, v97
	v_add_f32_e32 v67, v72, v67
	v_add_f32_e32 v120, v129, v120
	v_add_f32_e32 v121, v145, v121
	v_add_f32_e32 v97, v160, v97
	v_add_f32_e32 v67, v73, v67
	v_add_f32_e32 v120, v131, v120
	v_add_f32_e32 v121, v146, v121
	v_add_f32_e32 v97, v161, v97
	v_add_f32_e32 v67, v74, v67
	v_add_f32_e32 v120, v132, v120
	v_add_f32_e32 v121, v147, v121
	v_add_f32_e32 v97, v162, v97
	v_add_f32_e32 v67, v75, v67
	v_add_f32_e32 v120, v133, v120
	v_add_f32_e32 v121, v148, v121
	v_add_f32_e32 v97, v163, v97
	v_add_f32_e32 v67, v76, v67
	v_add_f32_e32 v120, v134, v120
	v_add_f32_e32 v121, v149, v121
	v_add_f32_e32 v97, v164, v97
	v_add_f32_e32 v67, v77, v67
	v_add_f32_e32 v120, v135, v120
	v_add_f32_e32 v121, v150, v121
	v_add_f32_e32 v97, v165, v97
	v_add_f32_e32 v67, v79, v67
	v_add_f32_e32 v120, v136, v120
	v_add_f32_e32 v121, v151, v121
	v_add_f32_e32 v97, v166, v97
	v_add_f32_e32 v67, v81, v67
	v_add_f32_e32 v120, v130, v120
	v_add_f32_e32 v121, v152, v121
	v_add_f32_e32 v97, v167, v97
	v_add_f32_e32 v67, v169, v67
	v_fmac_f32_e32 v121, v120, v102
	v_add_f32_e32 v97, v168, v97
	v_add_f32_e32 v67, v80, v67
	v_fmac_f32_e32 v97, v121, v104
	v_add_f32_e32 v132, v78, v67
	s_andn2_b64 vcc, exec, s[0:1]
	v_fmac_f32_e32 v132, v97, v66
	s_cbranch_vccnz .LBB0_774
	v_ashrrev_i32_e32 v66, 8, v94
	v_add_u32_e32 v67, s78, v66
	v_and_b32_e32 v68, 48, v118
	v_or_b32_e32 v69, v68, v117
	v_max_i32_e32 v67, 4, v67
	v_sub_u32_e64 v69, v69, 8 clamp
	v_add_u32_e32 v67, -4, v67
	v_min_u32_e32 v69, 48, v69
	v_min_u32_e32 v94, 56, v67
	v_or_b32_e32 v67, 1, v93
	v_cmp_ge_u32_e64 s[40:41], v67, v69
	v_or_b32_e32 v67, 2, v93
	v_cmp_ge_u32_e64 s[42:43], v67, v69
	v_or_b32_e32 v67, 3, v93
	v_cmp_ge_u32_e64 s[44:45], v67, v69
	v_or_b32_e32 v67, 17, v93
	v_cmp_lt_u32_e64 s[0:1], v67, v69
	v_or_b32_e32 v67, 18, v93
	v_cmp_lt_u32_e64 s[54:55], v67, v69
	v_or_b32_e32 v67, 19, v93
	v_cmp_lt_u32_e64 s[56:57], v67, v69
	v_or_b32_e32 v67, 33, v93
	v_cmp_lt_u32_e64 s[48:49], v67, v69
	v_cmp_ge_u32_e64 s[60:61], v67, v69
	v_or_b32_e32 v67, 34, v93
	v_cmp_lt_u32_e64 s[50:51], v67, v69
	v_cmp_ge_u32_e64 s[62:63], v67, v69
	v_or_b32_e32 v67, 35, v93
	s_nor_b64 s[36:37], s[0:1], s[40:41]
	s_and_b64 s[60:61], s[60:61], s[0:1]
	s_lshl_b32 s0, s95, 6
	v_sub_u32_e32 v66, s95, v66
	v_cmp_lt_u32_e64 s[52:53], v67, v69
	v_cmp_ge_u32_e64 s[64:65], v67, v69
	s_add_i32 s6, s0, 0x180
	v_sub_u32_e32 v67, v93, v117
	v_subrev_u32_e32 v66, s78, v66
	s_movk_i32 s0, 0x7c
	v_sub_u32_e32 v67, v67, v68
	v_mul_lo_u32 v66, v66, s0
	v_add_u32_e32 v104, 16, v66
	v_add_u32_e32 v66, 64, v67
	v_min_u32_e32 v66, 30, v66
	v_lshlrev_b32_e32 v117, 2, v66
	v_add_u32_e32 v66, 0x41, v67
	v_min_u32_e32 v66, 30, v66
	v_lshlrev_b32_e32 v118, 2, v66
	v_add_u32_e32 v66, 0x42, v67
	v_min_u32_e32 v66, 30, v66
	v_lshlrev_b32_e32 v119, 2, v66
	v_add_u32_e32 v66, 35, v67
	v_max_i32_e32 v66, -15, v66
	v_add_u32_e32 v66, 15, v66
	v_min_u32_e32 v66, 30, v66
	v_lshlrev_b32_e32 v120, 2, v66
	v_add_u32_e32 v66, 34, v67
	v_max_i32_e32 v66, -15, v66
	v_add_u32_e32 v66, 15, v66
	v_min_u32_e32 v66, 30, v66
	v_lshlrev_b32_e32 v121, 2, v66
	v_add_u32_e32 v66, 33, v67
	v_max_i32_e32 v66, -15, v66
	v_add_u32_e32 v66, 15, v66
	v_min_u32_e32 v66, 30, v66
	v_lshlrev_b32_e32 v122, 2, v66
	v_add_u32_e32 v66, 32, v67
	v_max_i32_e32 v66, -15, v66
	v_add_u32_e32 v66, 15, v66
	v_min_u32_e32 v66, 30, v66
	v_lshlrev_b32_e32 v123, 2, v66
	v_add_u32_e32 v66, 19, v67
	v_max_i32_e32 v66, -15, v66
	v_add_u32_e32 v66, 15, v66
	v_min_u32_e32 v66, 30, v66
	v_lshlrev_b32_e32 v124, 2, v66
	v_add_u32_e32 v66, 18, v67
	v_max_i32_e32 v66, -15, v66
	v_add_u32_e32 v66, 15, v66
	v_min_u32_e32 v66, 30, v66
	v_lshlrev_b32_e32 v125, 2, v66
	v_add_u32_e32 v66, 17, v67
	v_max_i32_e32 v66, -15, v66
	v_add_u32_e32 v66, 15, v66
	v_min_u32_e32 v66, 30, v66
	v_lshlrev_b32_e32 v126, 2, v66
	v_add_u32_e32 v66, 16, v67
	v_max_i32_e32 v66, -15, v66
	v_add_u32_e32 v66, 15, v66
	v_min_u32_e32 v66, 30, v66
	v_lshlrev_b32_e32 v127, 2, v66
	v_add_u32_e32 v66, 3, v67
	v_max_i32_e32 v66, -15, v66
	v_lshlrev_b32_e32 v128, 2, v66
	v_add_u32_e32 v66, 2, v67
	v_max_i32_e32 v66, -15, v66
	v_lshlrev_b32_e32 v129, 2, v66
	v_add_u32_e32 v66, 1, v67
	v_add_u32_e32 v68, 63, v67
	v_max_i32_e32 v66, -15, v66
	v_cmp_ge_u32_e64 s[38:39], v93, v69
	v_cmp_lt_u32_e32 vcc, v96, v69
	v_cmp_ge_u32_e64 s[58:59], v92, v69
	v_min_u32_e32 v68, 30, v68
	v_lshlrev_b32_e32 v130, 2, v66
	v_max_i32_e32 v66, -15, v67
	s_mov_b32 s75, s77
	s_mov_b32 s20, s76
	s_mov_b32 s9, s11
	s_add_i32 s4, s3, 3
	s_add_i32 s5, s3, 5
	v_add_u32_e32 v97, 8, v94
	s_nor_b64 s[34:35], vcc, s[38:39]
	v_cmp_lt_u32_e64 s[46:47], v92, v69
	s_nor_b64 s[72:73], s[54:55], s[42:43]
	s_nor_b64 s[76:77], s[56:57], s[44:45]
	s_and_b64 s[58:59], s[58:59], vcc
	s_and_b64 s[54:55], s[62:63], s[54:55]
	s_and_b64 s[56:57], s[64:65], s[56:57]
	s_add_i32 s7, s2, 8
	v_lshlrev_b32_e32 v102, 2, v68
	v_lshlrev_b32_e32 v131, 2, v66
	s_mov_b32 s8, 0
	v_readfirstlane_b32 s99, v171
	s_nop 3
	s_cmp_lt_u32 s99, 0x100
	s_cbranch_scc1 .Lna_prio_skip
	s_setprio 1
.Lna_prio_skip:
	s_branch .LBB0_728
.LBB0_727:
	s_add_i32 s6, s6, 64
	s_add_i32 s8, s8, 1
	s_cmp_lg_u32 s7, s8
	v_add_u32_e32 v104, 0x7c, v104
	s_cbranch_scc0 .LBB0_775

; template <int DQK, int QT, bool NA> ...
;     ...
;     for (int ti = 4; ti < ntile; ++ti) tile_iter(ti);
;   }
;   const u16* proj = (const u16*)(ws + O_PROJ);
.LBB0_775:
	s_setprio 0
	s_mov_b64 s[14:15], 0xa28c080
	s_mov_b64 s[16:17], 0x2223c800
	s_mov_b32 s11, s9
	s_mov_b32 s76, s20
	s_mov_b32 s77, s75
